# blocks 32..255 interleave their weight-conversion units between their attention units
# baseline (speedup 1.0000x reference)
; DI void phase_m2(const Params& p, int l, int bid, int nb, h16* lds) {
;     ...
;   const int ustart = (bid < 32) ? bid : bid;
;   const int ustep = (bid < 32) ? total : (nb - 32);
;   for (int u = ustart; u < total; u += ustep) {
;     int v = u;
;     if (v >= 5288) { v -= 5288; if (v < nA) conv_one(p, l, 2560 + v, lds); else conv_one(p, l + 1, v - nA, lds); continue; }
.LBB0_892:
	s_and_b64 s[2:3], exec, s[2:3]
	s_movk_i32 s2, 0x2700
	s_cselect_b32 s91, s2, 0x5880
	v_readlane_b32 s2, v255, 30
	v_readlane_b32 s4, v255, 32
	v_readlane_b32 s3, v255, 31
	s_add_i32 s2, s4, 1
	v_readlane_b32 s5, v255, 33
	v_writelane_b32 v255, s2, 30
	s_cmp_lg_u32 s4, 3
	s_nop 0
	v_writelane_b32 v255, s3, 31
	s_cselect_b64 s[2:3], -1, 0
	v_writelane_b32 v255, s2, 36
	s_cmp_eq_u32 s4, 3
	s_nop 0
	v_writelane_b32 v255, s3, 37
	s_movk_i32 s2, 0xaa8
	s_cselect_b32 s2, s2, 0x14a8
	s_add_i32 s90, s91, s2
	v_cmp_gt_i32_e32 vcc, s90, v1
	s_and_saveexec_b64 s[64:65], vcc
	s_cbranch_execz .LBB0_1028
	v_readlane_b32 s16, v255, 32
	v_readlane_b32 s68, v255, 30
	v_readlane_b32 s2, v254, 31
	v_readlane_b32 s17, v255, 33
	v_readlane_b32 s69, v255, 31
	v_mov_b32_e32 v2, s2
	s_lshr_b32 s2, s68, 1
	s_mov_b32 s17, s69
	s_lshr_b32 s4, s16, 1
	v_readlane_b32 s36, v252, 11
	s_addk_i32 s91, 0xf600
	s_lshl_b32 s92, s16, 3
	s_mul_hi_u32 s6, s68, 0x2420000
	s_mul_i32 s7, s68, 0x2420000
	s_mul_i32 s66, s2, 0xb00000
	s_lshl_b32 s93, s2, 3
	s_lshl_b64 s[2:3], s[68:69], 22
	s_lshl_b32 s94, s4, 3
	s_mul_i32 s68, s4, 0xb00000
	s_lshl_b64 s[4:5], s[16:17], 22
	v_readlane_b32 s38, v252, 13
	v_readlane_b32 s48, v252, 23
	v_readlane_b32 s49, v252, 24
	v_readlane_b32 s50, v252, 25
	v_readlane_b32 s51, v252, 26
	v_readlane_b32 s39, v252, 14
	s_add_u32 s70, s38, s7
	v_readlane_b32 s48, v252, 43
	v_readlane_b32 s40, v252, 15
	v_readlane_b32 s41, v252, 16
	v_readlane_b32 s42, v252, 17
	v_readlane_b32 s43, v252, 18
	v_readlane_b32 s44, v252, 19
	v_readlane_b32 s45, v252, 20
	v_readlane_b32 s46, v252, 21
	v_readlane_b32 s47, v252, 22
	s_addc_u32 s71, s39, s6
	v_readlane_b32 s49, v252, 44
	v_readlane_b32 s50, v252, 45
	v_readlane_b32 s51, v252, 46
	v_readlane_b32 s52, v252, 47
	v_readlane_b32 s53, v252, 48
	v_readlane_b32 s54, v252, 49
	v_readlane_b32 s55, v252, 50
	v_readlane_b32 s56, v252, 51
	v_readlane_b32 s57, v252, 52
	s_add_u32 s72, s56, s66
	v_readlane_b32 s40, v252, 27
	s_addc_u32 s73, s57, 0
	v_readlane_b32 s50, v252, 37
	v_readlane_b32 s51, v252, 38
	s_add_u32 s74, s50, s2
	s_addc_u32 s75, s51, s3
	s_add_u32 s76, s56, s68
	s_addc_u32 s77, s57, 0
	s_add_u32 s78, s50, s4
	v_mov_b32_e32 v3, s90
	v_cmp_gt_i32_e32 vcc, 32, v1
	s_mul_hi_u32 s8, s16, 0x2420000
	v_writelane_b32 v255, s16, 32
	s_mul_i32 s9, s16, 0x2420000
	s_addc_u32 s79, s51, s5
	v_cndmask_b32_e32 v161, v2, v3, vcc
	s_add_u32 s80, s38, s9
	s_mov_b32 s67, s69
	v_writelane_b32 v255, s17, 33
	s_addc_u32 s81, s39, s8
	v_lshlrev_b32_e32 v162, 3, v1
	v_lshlrev_b32_e32 v163, 3, v161
	v_lshlrev_b32_e32 v164, 10, v1
	v_lshlrev_b32_e32 v165, 10, v161
	v_lshrrev_b32_e32 v162, 1, v181
	v_and_b32_e32 v163, 1, v181
	v_mov_b32_e32 v1, v181
	v_mov_b32_e32 v161, 0x1c0
	v_add_u32_e32 v215, 32, v162
	v_cmp_eq_u32_e32 vcc, 1, v163
	v_cndmask_b32_e32 v215, v162, v215, vcc
	v_mov_b32_e32 v165, s90
	v_cmp_gt_u32_e32 vcc, 32, v162
	v_cndmask_b32_e32 v1, v1, v215, vcc
	v_cndmask_b32_e32 v161, v161, v165, vcc
	v_lshlrev_b32_e32 v164, 10, v1
	v_mov_b32_e32 v162, 1
	v_mov_b32_e32 v163, 0
	v_mov_b32_e32 v165, 0
	s_mov_b64 s[82:83], 0
	v_readlane_b32 s37, v252, 12
	v_readlane_b32 s58, v252, 53
	v_readlane_b32 s59, v252, 54
	v_readlane_b32 s60, v252, 55
	v_readlane_b32 s61, v252, 56
	v_readlane_b32 s62, v252, 57
	v_readlane_b32 s63, v252, 58
	v_readlane_b32 s41, v252, 28
	v_readlane_b32 s42, v252, 29
	v_readlane_b32 s43, v252, 30
	v_readlane_b32 s44, v252, 31
	v_readlane_b32 s45, v252, 32
	v_readlane_b32 s46, v252, 33
	v_readlane_b32 s47, v252, 34
	v_readlane_b32 s48, v252, 35
	v_readlane_b32 s49, v252, 36
	v_readlane_b32 s52, v252, 39
	v_readlane_b32 s53, v252, 40
	v_readlane_b32 s54, v252, 41
	v_readlane_b32 s55, v252, 42
	s_branch .LBB0_897

; DI void phase_m2(const Params& p, int l, int bid, int nb, h16* lds) {
;     ...
;   for (int u = ustart; u < total; u += ustep) {
;     int v = u;
;     if (v >= 5288) { v -= 5288; if (v < nA) conv_one(p, l, 2560 + v, lds); else conv_one(p, l + 1, v - nA, lds); continue; }
.LBB0_896:
	s_or_b64 exec, exec, s[4:5]
	v_readfirstlane_b32 s36, v161
	s_nop 1
	s_cmp_eq_u32 s36, 0x1c0
	s_cbranch_scc0 .Lil_static
	v_readfirstlane_b32 s36, v162
	v_readfirstlane_b32 s37, v163
	v_readfirstlane_b32 s38, v165
	v_readfirstlane_b32 s39, v181
	s_nop 1
	s_and_b32 s46, s39, -2
	s_sub_u32 s47, 0x1667, s46
	s_mul_i32 s47, s47, 0x924a
	s_lshr_b32 s47, s47, 24
	s_mul_i32 s45, s47, 448
	s_add_u32 s45, s45, s46
	s_sub_u32 s45, s90, s45
	s_add_u32 s45, s45, 447
	s_mul_i32 s45, s45, 0x924a
	s_lshr_b32 s45, s45, 24
	s_add_u32 s45, s45, s47
	s_sub_u32 s45, s45, 1
	s_mul_i32 s44, s45, 0xba2f
	s_lshr_b32 s44, s44, 19
	s_mul_i32 s45, s45, 0xaaab
	s_lshr_b32 s45, s45, 19
	s_cmp_eq_u32 s47, 11
	s_cselect_b32 s45, s44, s45
	s_cmp_eq_u32 s37, 0
	s_cselect_b32 s38, s45, s38
	s_cselect_b32 s37, s47, s37
	s_mul_i32 s40, s37, 448
	s_add_u32 s40, s40, s39
	s_cmp_lt_u32 s40, s90
	s_cselect_b32 s41, 1, 0
	s_cmp_gt_u32 s38, 0
	s_cselect_b32 s42, 1, 0
	s_and_b32 s42, s42, s41
	s_cmp_eq_u32 s42, 1
	s_cbranch_scc1 .Lil_conv_g
	s_cmp_lt_u32 s36, s47
	s_cbranch_scc1 .Lil_attn
	s_cmp_eq_u32 s41, 1
	s_cbranch_scc1 .Lil_conv
	s_mov_b32 s44, s90
	s_branch .Lil_set
.Lil_conv_g:
	s_sub_u32 s38, s38, 1
.Lil_conv:
	s_mov_b32 s44, s40
	s_add_u32 s37, s37, 1
	s_branch .Lil_set
.Lil_attn:
	s_mul_i32 s44, s36, 448
	s_add_u32 s44, s44, s39
	s_add_u32 s36, s36, 1
	s_mov_b32 s38, s45
.Lil_set:
	v_mov_b32_e32 v1, s44
	v_mov_b32_e32 v162, s36
	v_mov_b32_e32 v163, s37
	v_mov_b32_e32 v165, s38
	s_branch .Lil_done

; template <int NKB>
; DI void attn_unit(const Params& p, int l, int mode, int grp, int head, int r0, int dil, int i0, int sub_len, int W, h16* lds) {
;   unsigned char* ws = p.ws;
;   const h16* P = (const h16*)(ws + OFF_PS);
;   h16* Qi = lds; h16* Ki = lds + 64 * LDH; h16* Vt = lds + 128 * LDH; h16* Pi = lds + 192 * LDH;
;   const int tid = otid(), lane = tid & 63, w = tid >> 6, r = lane & 15, q = lane >> 4;
;   const int lrow = tid >> 2, seg = tid & 3;
;   int qcol, kcol, vcol;
;   if (mode == 0) { qcol = 1024 + grp * 256 + head * 64; kcol = 1792 + grp * 256 + head * 64; vcol = 2560 + grp * 256 + head * 64; }
;   else { qcol = 4352 + head * 64; kcol = 4864 + (head >> 2) * 64; vcol = 4992 + (head >> 2) * 64; }
;   __syncthreads();
;   {
;     const size_t pos = (size_t)r0 + (size_t)dil * (i0 + lrow);
;     const h16* g = P + pos * NSM + qcol + 16 * seg;
;     img_store_nat(Qi, lrow, seg, *(const u4v*)g, *(const u4v*)(g + 8));
;   }
;   float mrow[4], lsum[4];
;   f4v O[4];
;   float m_init = -1e30f, l_init = 0.f;
;   if (mode == 1) { m_init = p.d_sink[l * 8 + head]; l_init = 1.f; }
; #pragma unroll
;   for (int i = 0; i < 4; ++i) { mrow[i] = m_init; lsum[i] = l_init; O[i] = (f4v){0.f, 0.f, 0.f, 0.f}; }
;   u4v pk0, pk1, pv0, pv1;
;     ...
;   ATT_PREFETCH(0);
;   for (int kb = 0; kb < NKB; ++kb) {
;     const int j0 = i0 - W + 64 * kb;
;     const bool inr = (j0 >= 0) && (j0 < sub_len);
;     __syncthreads();
;     img_store_nat(Ki, lrow, seg, pk0, pk1);
;     img_store_T(Vt, lrow, seg, pv0, pv1);
;     __syncthreads();
; DI void phase_m2(const Params& p, int l, int bid, int nb, h16* lds) {
;     ...
;   for (int u = ustart; u < total; u += ustep) {
;     int v = u;
;     if (v >= 5288) { v -= 5288; if (v < nA) conv_one(p, l, 2560 + v, lds); else conv_one(p, l + 1, v - nA, lds); continue; }
;     if (v < 32) { dn_c2_unit(p, v >> 2, v & 3); continue; }
;     if ((v -= 32) < 136) { mlstm_a2_unit(p, v); continue; }
;     if ((v -= 136) < 2048) { attn_unit<5>(p, l, 1, 0, v & 7, 0, 1, (v >> 3) * 64, SEQ, 128, lds); continue; }
;     v -= 2048;
;     const int grp = v >> 10, x = v & 1023, head = x & 3, tl = x >> 2;
;     const int dil = (grp == 0) ? 1 : (grp == 1) ? 4 : 16;
;     const int sub = SEQ / dil, tps = sub >> 6;
;     const int res = tl / tps, ti = tl % tps;
;     attn_unit<3>(p, l, 0, grp, head, res, dil, ti * 64, sub, 64, lds);
.LBB0_897:
	s_movk_i32 s2, 0x14a8
	v_cmp_gt_i32_e32 vcc, s2, v1
	s_and_saveexec_b64 s[2:3], vcc
	s_xor_b64 s[84:85], exec, s[2:3]
	s_cbranch_execz .LBB0_960
	v_cmp_lt_i32_e32 vcc, 31, v1
	s_and_saveexec_b64 s[2:3], vcc
	s_xor_b64 s[86:87], exec, s[2:3]
	s_cbranch_execz .LBB0_953
	s_movk_i32 s2, 0xa7
	v_cmp_lt_u32_e32 vcc, s2, v1
	s_and_saveexec_b64 s[2:3], vcc
	s_xor_b64 s[88:89], exec, s[2:3]
	s_cbranch_execz .LBB0_915
	s_movk_i32 s2, 0x8a7
	v_cmp_lt_u32_e32 vcc, s2, v1
	s_and_saveexec_b64 s[2:3], vcc
	s_xor_b64 s[34:35], exec, s[2:3]
	s_cbranch_execz .LBB0_910
	v_readfirstlane_b32 s36, v1
	v_readfirstlane_b32 s58, v182
	s_lshr_b32 s58, s58, 6
	s_sub_u32 s51, s36, 0x8a8
	s_and_b32 s56, s51, 15
	s_sub_u32 s56, s56, 8
	s_and_b32 s56, s56, 15
	s_lshr_b32 s56, s56, 1
	s_lshr_b32 s57, s51, 4
	s_lshl_b32 s57, s57, 1
	s_and_b32 s59, s51, 1
	s_or_b32 s57, s57, s59
	s_mul_i32 s59, s57, 0xaaab
	s_lshr_b32 s59, s59, 19
	s_mul_i32 s62, s59, 12
	s_sub_u32 s62, s57, s62
	s_lshr_b32 s61, s62, 2
	s_and_b32 s37, s62, 3
	s_lshl_b32 s62, s56, 5
	s_add_u32 s62, s62, s59
	s_lshl_b32 s63, s61, 1
	s_lshl_b32 s60, 1, s63
	s_movk_i32 s39, 0x2800
	s_lshl_b32 s39, s39, s63
	s_movk_i32 s41, 0x4000
	s_lshr_b32 s41, s41, s63
	s_sub_u32 s51, 8, s63
	s_lshr_b32 s40, s62, s51
	s_movk_i32 s51, 0x100
	s_lshr_b32 s51, s51, s63
	s_sub_u32 s51, s51, 1
	s_and_b32 s38, s62, s51
	s_lshl_b32 s38, s38, 6
	s_lshl_b32 s51, s61, 9
	s_lshl_b32 s56, s37, 7
	s_add_u32 s51, s51, s56
	s_add_u32 s53, s51, 0x800
	s_add_u32 s54, s51, 0xe00
	s_add_u32 s55, s51, 0x1400
	v_and_b32_e32 v179, 63, v182
	v_and_b32_e32 v200, 15, v179
	v_lshrrev_b32_e32 v201, 4, v179
	v_lshlrev_b32_e32 v202, 4, v201
	v_mad_u32_u24 v2, v200, s39, v202
	v_add_u32_e32 v203, 16, v200
	v_mad_u32_u24 v3, v203, s39, v202
	v_add_u32_e32 v203, 32, v200
	v_mad_u32_u24 v4, v203, s39, v202
	v_add_u32_e32 v203, 48, v200
	v_mad_u32_u24 v5, v203, s39, v202
	s_lshl_b32 s51, s58, 4
	v_add_u32_e32 v203, s51, v200
	v_mad_u32_u24 v248, v203, s39, v202
	v_lshlrev_b32_e32 v160, 2, v201
	v_sub_u32_e32 v160, v160, v203
	s_lshl_b32 s51, s60, 9
	v_mul_u32_u24_e32 v249, s51, v203
	s_lshl_b32 s51, s60, 5
	v_mul_u32_u24_e32 v203, s51, v203
	v_lshl_add_u32 v249, v201, 3, v249
	v_lshrrev_b32_e32 v203, 3, v179
	s_lshl_b32 s51, s58, 4
	v_add_u32_e32 v203, s51, v203
	v_and_b32_e32 v202, 7, v179
	v_lshlrev_b32_e32 v202, 4, v202
	v_mad_u32_u24 v6, v203, s39, v202
	v_add_u32_e32 v200, 8, v203
	v_mad_u32_u24 v7, v200, s39, v202
	s_movk_i32 s57, 0x90
	v_mad_u32_u24 v158, v203, s57, v183
	v_add_u32_e32 v158, v158, v202
	v_and_b32_e32 v200, 15, v179
	v_mad_u32_u24 v8, v200, s57, v183
	v_lshl_add_u32 v8, v201, 4, v8
	v_lshrrev_b32_e32 v203, 2, v179
	v_mad_u32_u24 v159, v203, s57, v183
	v_and_b32_e32 v203, 3, v179
	v_lshl_add_u32 v159, v203, 3, v159
	v_add_u32_e32 v159, 0x2400, v159
	v_xor_b32_e32 v174, 16, v179
	v_lshlrev_b32_e32 v174, 2, v174
	v_xor_b32_e32 v175, 32, v179
	v_lshlrev_b32_e32 v175, 2, v175
	s_mul_i32 s51, s60, s38
	s_add_u32 s51, s51, s40
	s_mul_i32 s56, s51, 0x2800
	s_add_u32 s56, s56, s53
	s_add_u32 s42, s0, s56
	s_addc_u32 s43, s1, 0
	global_load_dwordx4 v[10:13], v248, s[42:43]
	global_load_dwordx4 v[14:17], v248, s[42:43] offset:64
	v_readlane_b32 s48, v254, 32
	v_readlane_b32 s49, v254, 33
	v_readlane_b32 s16, v254, 34
	v_readlane_b32 s17, v254, 35
	s_lshl_b32 s56, s61, 14
	s_add_u32 s56, s56, s51
	s_lshl_b32 s57, s56, 9
	s_lshl_b32 s59, s37, 7
	s_add_u32 s57, s57, s59
	s_add_u32 s48, s48, s57
	s_addc_u32 s49, s49, 0
	s_lshl_b32 s57, s56, 5
	s_lshl_b32 s59, s37, 3
	s_add_u32 s57, s57, s59
	s_add_u32 s16, s16, s57
	s_addc_u32 s17, s17, 0
	v_mov_b32_e32 v176, 0xf149f2ca
	v_mov_b32_e32 v177, 0
	v_mov_b32_e32 v138, 0
	v_mov_b32_e32 v139, 0
	v_mov_b32_e32 v140, 0
	v_mov_b32_e32 v141, 0
	v_mov_b32_e32 v142, 0
	v_mov_b32_e32 v143, 0
	v_mov_b32_e32 v144, 0
	v_mov_b32_e32 v145, 0
	v_mov_b32_e32 v146, 0
	v_mov_b32_e32 v147, 0
	v_mov_b32_e32 v148, 0
	v_mov_b32_e32 v149, 0
	v_mov_b32_e32 v150, 0
	v_mov_b32_e32 v151, 0
	v_mov_b32_e32 v152, 0
	v_mov_b32_e32 v153, 0
	s_sub_u32 s50, s38, 64
	s_cmp_ge_i32 s50, 0
	s_cselect_b32 s56, 1, 0
	s_cmp_lt_i32 s50, s41
	s_cselect_b32 s57, 1, 0
	s_and_b32 s2, s56, s57
	s_cmp_eq_u32 s2, 1
	s_cselect_b32 s50, s50, s38
	s_mul_i32 s50, s50, s60
	s_add_u32 s50, s50, s40
	s_mul_i32 s50, s50, 0x2800
	s_add_u32 s56, s50, s54
	s_add_u32 s44, s0, s56
	s_addc_u32 s45, s1, 0
	s_add_u32 s56, s50, s55
	s_add_u32 s46, s0, s56
	s_addc_u32 s47, s1, 0
	global_load_dwordx4 v[50:53], v6, s[44:45]
	global_load_dwordx4 v[54:57], v7, s[44:45]
	global_load_dwordx4 v[58:61], v6, s[46:47]
	global_load_dwordx4 v[62:65], v7, s[46:47]
	s_add_u32 s50, s38, 0
	s_cmp_ge_i32 s50, 0
	s_cselect_b32 s56, 1, 0
	s_cmp_lt_i32 s50, s41
	s_cselect_b32 s57, 1, 0
	s_and_b32 s3, s56, s57
	s_cmp_eq_u32 s3, 1
	s_cselect_b32 s50, s50, s38
	s_mul_i32 s50, s50, s60
	s_add_u32 s50, s50, s40
	s_mul_i32 s50, s50, 0x2800
	s_add_u32 s56, s50, s54
	s_add_u32 s44, s0, s56
	s_addc_u32 s45, s1, 0
	s_add_u32 s56, s50, s55
	s_add_u32 s46, s0, s56
	s_addc_u32 s47, s1, 0
	global_load_dwordx4 v[66:69], v6, s[44:45]
	global_load_dwordx4 v[70:73], v7, s[44:45]
	global_load_dwordx4 v[74:77], v6, s[46:47]
	global_load_dwordx4 v[78:81], v7, s[46:47]
	s_waitcnt vmcnt(4)
	s_barrier
	ds_write_b128 v158, v[50:53] offset:0
	ds_write_b128 v158, v[54:57] offset:1152
	ds_write_b128 v158, v[58:61] offset:9216
	ds_write_b128 v158, v[62:65] offset:10368
	s_waitcnt lgkmcnt(0)
	s_barrier
; template <int NKB>
; DI void attn_unit(const Params& p, int l, int mode, int grp, int head, int r0, int dil, int i0, int sub_len, int W, h16* lds) {
;     ...
;   ATT_PREFETCH(0);
;   for (int kb = 0; kb < NKB; ++kb) {
;     const int j0 = i0 - W + 64 * kb;
;     const bool inr = (j0 >= 0) && (j0 < sub_len);
;     __syncthreads();
;     img_store_nat(Ki, lrow, seg, pk0, pk1);
;     img_store_T(Vt, lrow, seg, pv0, pv1);
;     __syncthreads();
;     if (kb + 1 < NKB) ATT_PREFETCH(kb + 1);
	s_add_u32 s50, s38, 64
	s_cmp_ge_i32 s50, 0
	s_cselect_b32 s56, 1, 0
	s_cmp_lt_i32 s50, s41
	s_cselect_b32 s57, 1, 0
	s_and_b32 s4, s56, s57
	s_cmp_eq_u32 s4, 1
	s_cselect_b32 s50, s50, s38
	s_mul_i32 s50, s50, s60
	s_add_u32 s50, s50, s40
	s_mul_i32 s50, s50, 0x2800
	s_add_u32 s56, s50, s54
	s_add_u32 s44, s0, s56
	s_addc_u32 s45, s1, 0
	s_add_u32 s56, s50, s55
	s_add_u32 s46, s0, s56
	s_addc_u32 s47, s1, 0
	global_load_dwordx4 v[50:53], v6, s[44:45]
	global_load_dwordx4 v[54:57], v7, s[44:45]
	global_load_dwordx4 v[58:61], v6, s[46:47]
	global_load_dwordx4 v[62:65], v7, s[46:47]
	s_cmp_eq_u32 s2, 1
	s_cbranch_scc0 .Lat0_kb0_end
; DI float grp16_sum(float v) { v += __shfl_xor(v, 1); v += __shfl_xor(v, 2); v += __shfl_xor(v, 4); v += __shfl_xor(v, 8); return v; }
; DI float grp16_max(float v) { v = fmaxf(v, __shfl_xor(v, 1)); v = fmaxf(v, __shfl_xor(v, 2)); v = fmaxf(v, __shfl_xor(v, 4)); v = fmaxf(v, __shfl_xor(v, 8)); return v; }
; template <int NKB>
; DI void attn_unit(const Params& p, int l, int mode, int grp, int head, int r0, int dil, int i0, int sub_len, int W, h16* lds) {
;     ...
;     f4v S[4];
; #pragma unroll
;     for (int i = 0; i < 4; ++i) S[i] = (f4v){0.f, 0.f, 0.f, 0.f};
;     mm64(Qi, Ki, S, w, lane);
;     float mx[4], al[4], rsum[4];
;     bool vm[4][4];
; #pragma unroll
;     for (int rg = 0; rg < 4; ++rg) {
;       const int row = 16 * w + 4 * q + rg;
;       float m_ = -1e30f;
; #pragma unroll
;       for (int nt = 0; nt < 4; ++nt) {
;         const int key = 16 * nt + r;
;         const int delta = row - key + W - 64 * kb;
;         const bool ok = inr && (delta >= -W) && (delta <= W);
;         vm[nt][rg] = ok;
;         float s = S[nt][rg] * 0.125f;
;         S[nt][rg] = s;
;         if (ok) m_ = fmaxf(m_, s);
;       }
;       mx[rg] = grp16_max(m_);
;     }
; #pragma unroll
;     for (int rg = 0; rg < 4; ++rg) {
;       const float mn = fmaxf(mrow[rg], mx[rg]);
;       al[rg] = __expf(mrow[rg] - mn);
;       mrow[rg] = mn;
;       float rs_ = 0.f;
; #pragma unroll
;       for (int nt = 0; nt < 4; ++nt) {
;         float pv = vm[nt][rg] ? __expf(S[nt][rg] - mn) : 0.f;
;         rs_ += pv;
;         Pi[(16 * w + 4 * q + rg) * LDH + 16 * nt + r] = (h16)pv;
;       }
;       rsum[rg] = grp16_sum(rs_);
;       lsum[rg] = lsum[rg] * al[rg] + rsum[rg];
;     }
; #pragma unroll
;     for (int et = 0; et < 4; ++et)
; #pragma unroll
;       for (int rg = 0; rg < 4; ++rg) O[et][rg] *= al[rg];
;     __syncthreads();
;     mm64(Pi, Vt, O, w, lane);
	ds_read_b128 v[18:21], v8 offset:0
	ds_read_b128 v[22:25], v8 offset:64
	ds_read_b128 v[26:29], v8 offset:2304
	ds_read_b128 v[30:33], v8 offset:2368
	ds_read_b128 v[34:37], v8 offset:4608
	ds_read_b128 v[38:41], v8 offset:4672
	ds_read_b128 v[42:45], v8 offset:6912
	ds_read_b128 v[46:49], v8 offset:6976
	ds_read_b64_tr_b16 v[216:217], v159
	ds_read_b64_tr_b16 v[218:219], v159 offset:2304
	ds_read_b64_tr_b16 v[220:221], v159 offset:4608
	ds_read_b64_tr_b16 v[222:223], v159 offset:6912
	ds_read_b64_tr_b16 v[224:225], v159 offset:32
	ds_read_b64_tr_b16 v[226:227], v159 offset:2336
	ds_read_b64_tr_b16 v[228:229], v159 offset:4640
	ds_read_b64_tr_b16 v[230:231], v159 offset:6944
	ds_read_b64_tr_b16 v[232:233], v159 offset:64
	ds_read_b64_tr_b16 v[234:235], v159 offset:2368
	ds_read_b64_tr_b16 v[236:237], v159 offset:4672
	ds_read_b64_tr_b16 v[238:239], v159 offset:6976
	ds_read_b64_tr_b16 v[240:241], v159 offset:96
	ds_read_b64_tr_b16 v[242:243], v159 offset:2400
	ds_read_b64_tr_b16 v[244:245], v159 offset:4704
	ds_read_b64_tr_b16 v[246:247], v159 offset:7008
	s_waitcnt lgkmcnt(15)
	v_mfma_f32_16x16x32_f16 v[114:117], v[18:21], v[10:13], 0
	v_mfma_f32_16x16x32_f16 v[118:121], v[26:29], v[10:13], 0
	v_mfma_f32_16x16x32_f16 v[122:125], v[34:37], v[10:13], 0
	v_mfma_f32_16x16x32_f16 v[126:129], v[42:45], v[10:13], 0
	v_mfma_f32_16x16x32_f16 v[114:117], v[22:25], v[14:17], v[114:117]
	v_mfma_f32_16x16x32_f16 v[118:121], v[30:33], v[14:17], v[118:121]
	v_mfma_f32_16x16x32_f16 v[122:125], v[38:41], v[14:17], v[122:125]
	v_mfma_f32_16x16x32_f16 v[126:129], v[46:49], v[14:17], v[126:129]
	s_nop 7
	s_nop 7
	v_mul_f32_e32 v114, 0x3e000000, v114
	v_mul_f32_e32 v115, 0x3e000000, v115
	v_mul_f32_e32 v116, 0x3e000000, v116
	v_mul_f32_e32 v117, 0x3e000000, v117
	v_mul_f32_e32 v118, 0x3e000000, v118
	v_mul_f32_e32 v119, 0x3e000000, v119
	v_mul_f32_e32 v120, 0x3e000000, v120
	v_mul_f32_e32 v121, 0x3e000000, v121
	v_mul_f32_e32 v122, 0x3e000000, v122
	v_mul_f32_e32 v123, 0x3e000000, v123
	v_mul_f32_e32 v124, 0x3e000000, v124
	v_mul_f32_e32 v125, 0x3e000000, v125
	v_mul_f32_e32 v126, 0x3e000000, v126
	v_mul_f32_e32 v127, 0x3e000000, v127
	v_mul_f32_e32 v128, 0x3e000000, v128
	v_mul_f32_e32 v129, 0x3e000000, v129
	v_mov_b32_e32 v200, 0xf149f2ca
	v_cmp_le_i32_e32 vcc, 0, v160
	v_cndmask_b32_e32 v114, v200, v114, vcc
	v_cmp_le_i32_e32 vcc, -1, v160
	v_cndmask_b32_e32 v115, v200, v115, vcc
	v_cmp_le_i32_e32 vcc, -2, v160
	v_cndmask_b32_e32 v116, v200, v116, vcc
	v_cmp_le_i32_e32 vcc, -3, v160
	v_cndmask_b32_e32 v117, v200, v117, vcc
	v_cmp_le_i32_e32 vcc, -16, v160
	v_cndmask_b32_e32 v118, v200, v118, vcc
	v_cmp_le_i32_e32 vcc, -17, v160
	v_cndmask_b32_e32 v119, v200, v119, vcc
	v_cmp_le_i32_e32 vcc, -18, v160
	v_cndmask_b32_e32 v120, v200, v120, vcc
	v_cmp_le_i32_e32 vcc, -19, v160
	v_cndmask_b32_e32 v121, v200, v121, vcc
	v_cmp_le_i32_e32 vcc, -32, v160
	v_cndmask_b32_e32 v122, v200, v122, vcc
	v_cmp_le_i32_e32 vcc, -33, v160
	v_cndmask_b32_e32 v123, v200, v123, vcc
	v_cmp_le_i32_e32 vcc, -34, v160
	v_cndmask_b32_e32 v124, v200, v124, vcc
	v_cmp_le_i32_e32 vcc, -35, v160
	v_cndmask_b32_e32 v125, v200, v125, vcc
	v_cmp_le_i32_e32 vcc, -48, v160
	v_cndmask_b32_e32 v126, v200, v126, vcc
	v_cmp_le_i32_e32 vcc, -49, v160
	v_cndmask_b32_e32 v127, v200, v127, vcc
	v_cmp_le_i32_e32 vcc, -50, v160
	v_cndmask_b32_e32 v128, v200, v128, vcc
	v_cmp_le_i32_e32 vcc, -51, v160
	v_cndmask_b32_e32 v129, v200, v129, vcc
	v_max3_f32 v179, v114, v115, v116
	v_max3_f32 v179, v179, v117, v118
	v_max3_f32 v179, v179, v119, v120
	v_max3_f32 v179, v179, v121, v122
	v_max3_f32 v179, v179, v123, v124
	v_max3_f32 v179, v179, v125, v126
	v_max3_f32 v179, v179, v127, v128
	v_max_f32_e32 v179, v179, v129
	ds_bpermute_b32 v201, v174, v179
	s_waitcnt lgkmcnt(0)
	v_max_f32_e32 v179, v179, v201
	ds_bpermute_b32 v201, v175, v179
	s_waitcnt lgkmcnt(0)
	v_max3_f32 v179, v179, v201, v176
	v_sub_f32_e32 v178, v176, v179
	v_mul_f32_e32 v178, 0x3fb8aa3b, v178
	v_exp_f32_e32 v178, v178
	v_mov_b32_e32 v176, v179
	v_mul_f32_e32 v202, 0xbfb8aa3b, v179
	v_mov_b32_e32 v203, 0x3fb8aa3b
	v_fma_f32 v114, v114, v203, v202
	v_fma_f32 v115, v115, v203, v202
	v_fma_f32 v116, v116, v203, v202
	v_fma_f32 v117, v117, v203, v202
	v_fma_f32 v118, v118, v203, v202
	v_fma_f32 v119, v119, v203, v202
	v_fma_f32 v120, v120, v203, v202
	v_fma_f32 v121, v121, v203, v202
	v_fma_f32 v122, v122, v203, v202
	v_fma_f32 v123, v123, v203, v202
	v_fma_f32 v124, v124, v203, v202
	v_fma_f32 v125, v125, v203, v202
	v_fma_f32 v126, v126, v203, v202
	v_fma_f32 v127, v127, v203, v202
	v_fma_f32 v128, v128, v203, v202
	v_fma_f32 v129, v129, v203, v202
	v_exp_f32_e32 v114, v114
	v_exp_f32_e32 v115, v115
	v_exp_f32_e32 v116, v116
	v_exp_f32_e32 v117, v117
	v_exp_f32_e32 v118, v118
	v_exp_f32_e32 v119, v119
	v_exp_f32_e32 v120, v120
	v_exp_f32_e32 v121, v121
	v_exp_f32_e32 v122, v122
	v_exp_f32_e32 v123, v123
	v_exp_f32_e32 v124, v124
	v_exp_f32_e32 v125, v125
	v_exp_f32_e32 v126, v126
	v_exp_f32_e32 v127, v127
	v_exp_f32_e32 v128, v128
	v_exp_f32_e32 v129, v129
	s_nop 0
	v_fma_f32 v177, v177, v178, v114
	v_add_f32_e32 v177, v177, v115
	v_add_f32_e32 v177, v177, v116
	v_add_f32_e32 v177, v177, v117
	v_add_f32_e32 v177, v177, v118
	v_add_f32_e32 v177, v177, v119
	v_add_f32_e32 v177, v177, v120
	v_add_f32_e32 v177, v177, v121
	v_add_f32_e32 v177, v177, v122
	v_add_f32_e32 v177, v177, v123
	v_add_f32_e32 v177, v177, v124
	v_add_f32_e32 v177, v177, v125
	v_add_f32_e32 v177, v177, v126
	v_add_f32_e32 v177, v177, v127
	v_add_f32_e32 v177, v177, v128
	v_add_f32_e32 v177, v177, v129
	v_cvt_pk_f16_f32 v130, v114, v115
	v_cvt_pk_f16_f32 v131, v116, v117
	v_cvt_pk_f16_f32 v132, v118, v119
	v_cvt_pk_f16_f32 v133, v120, v121
	v_cvt_pk_f16_f32 v134, v122, v123
	v_cvt_pk_f16_f32 v135, v124, v125
	v_cvt_pk_f16_f32 v136, v126, v127
	v_cvt_pk_f16_f32 v137, v128, v129
	v_pk_mul_f32 v[138:139], v[138:139], v[178:179] op_sel_hi:[1,0]
	v_pk_mul_f32 v[140:141], v[140:141], v[178:179] op_sel_hi:[1,0]
	v_pk_mul_f32 v[142:143], v[142:143], v[178:179] op_sel_hi:[1,0]
	v_pk_mul_f32 v[144:145], v[144:145], v[178:179] op_sel_hi:[1,0]
	v_pk_mul_f32 v[146:147], v[146:147], v[178:179] op_sel_hi:[1,0]
	v_pk_mul_f32 v[148:149], v[148:149], v[178:179] op_sel_hi:[1,0]
	v_pk_mul_f32 v[150:151], v[150:151], v[178:179] op_sel_hi:[1,0]
	v_pk_mul_f32 v[152:153], v[152:153], v[178:179] op_sel_hi:[1,0]
	s_nop 1
	v_mfma_f32_16x16x32_f16 v[138:141], v[216:219], v[130:133], v[138:141]
	v_mfma_f32_16x16x32_f16 v[142:145], v[224:227], v[130:133], v[142:145]
	v_mfma_f32_16x16x32_f16 v[146:149], v[232:235], v[130:133], v[146:149]
	v_mfma_f32_16x16x32_f16 v[150:153], v[240:243], v[130:133], v[150:153]
	v_mfma_f32_16x16x32_f16 v[138:141], v[220:223], v[134:137], v[138:141]
	v_mfma_f32_16x16x32_f16 v[142:145], v[228:231], v[134:137], v[142:145]
	v_mfma_f32_16x16x32_f16 v[146:149], v[236:239], v[134:137], v[146:149]
	v_mfma_f32_16x16x32_f16 v[150:153], v[244:247], v[134:137], v[150:153]

; DI int otid() { int t = threadIdx.x & 255; asm volatile("" : "+v"(t)); return t; }
; template <int NKB>
; DI void attn_unit(const Params& p, int l, int mode, int grp, int head, int r0, int dil, int i0, int sub_len, int W, h16* lds) {
;   unsigned char* ws = p.ws;
;   const h16* P = (const h16*)(ws + OFF_PS);
;   h16* Qi = lds; h16* Ki = lds + 64 * LDH; h16* Vt = lds + 128 * LDH; h16* Pi = lds + 192 * LDH;
;   const int tid = otid(), lane = tid & 63, w = tid >> 6, r = lane & 15, q = lane >> 4;
;   const int lrow = tid >> 2, seg = tid & 3;
;   int qcol, kcol, vcol;
;   if (mode == 0) { qcol = 1024 + grp * 256 + head * 64; kcol = 1792 + grp * 256 + head * 64; vcol = 2560 + grp * 256 + head * 64; }
;   else { qcol = 4352 + head * 64; kcol = 4864 + (head >> 2) * 64; vcol = 4992 + (head >> 2) * 64; }
;   __syncthreads();
;   {
;     const size_t pos = (size_t)r0 + (size_t)dil * (i0 + lrow);
;     const h16* g = P + pos * NSM + qcol + 16 * seg;
;     img_store_nat(Qi, lrow, seg, *(const u4v*)g, *(const u4v*)(g + 8));
;   }
;   float mrow[4], lsum[4];
;   f4v O[4];
;   float m_init = -1e30f, l_init = 0.f;
;   if (mode == 1) { m_init = p.d_sink[l * 8 + head]; l_init = 1.f; }
; #pragma unroll
;   for (int i = 0; i < 4; ++i) { mrow[i] = m_init; lsum[i] = l_init; O[i] = (f4v){0.f, 0.f, 0.f, 0.f}; }
;   u4v pk0, pk1, pv0, pv1;
;     ...
;   ATT_PREFETCH(0);
;   for (int kb = 0; kb < NKB; ++kb) {
;     const int j0 = i0 - W + 64 * kb;
;     const bool inr = (j0 >= 0) && (j0 < sub_len);
;     __syncthreads();
;     img_store_nat(Ki, lrow, seg, pk0, pk1);
;     img_store_T(Vt, lrow, seg, pv0, pv1);
;     __syncthreads();
;     if (kb + 1 < NKB) ATT_PREFETCH(kb + 1);
; DI void phase_m2(const Params& p, int l, int bid, int nb, h16* lds) {
;     ...
;     if ((v -= 136) < 2048) { attn_unit<5>(p, l, 1, 0, v & 7, 0, 1, (v >> 3) * 64, SEQ, 128, lds); continue; }
.LBB0_909:
.LBB0_910:
	s_andn2_saveexec_b64 s[34:35], s[34:35]
	s_cbranch_execz .LBB0_914
	v_readfirstlane_b32 s36, v1
	v_readfirstlane_b32 s58, v182
	s_lshr_b32 s58, s58, 6
	s_sub_u32 s51, s36, 0xa8
	s_and_b32 s56, s51, 15
	s_sub_u32 s56, s56, 8
	s_and_b32 s56, s56, 15
	s_lshr_b32 s56, s56, 1
	s_lshr_b32 s57, s51, 4
	s_lshl_b32 s57, s57, 1
	s_and_b32 s59, s51, 1
	s_or_b32 s57, s57, s59
	s_lshl_b32 s56, s56, 8
	s_add_u32 s36, s56, s57
	s_and_b32 s37, s36, 7
	s_lshr_b32 s38, s36, 3
	s_lshl_b32 s38, s38, 6
	s_mov_b32 s40, 0
	s_movk_i32 s39, 0x2800
	s_mov_b32 s60, 1
	s_movk_i32 s41, 0x4000
	s_lshr_b32 s51, s37, 2
	s_lshl_b32 s51, s51, 7
	s_lshl_b32 s56, s37, 7
	s_add_u32 s53, s56, 0x2200
	s_add_u32 s54, s51, 0x2600
	s_add_u32 s55, s51, 0x2700
	v_and_b32_e32 v179, 63, v182
	v_and_b32_e32 v200, 15, v179
	v_lshrrev_b32_e32 v201, 4, v179
	v_lshlrev_b32_e32 v202, 4, v201
	v_mad_u32_u24 v2, v200, s39, v202
	v_add_u32_e32 v203, 16, v200
	v_mad_u32_u24 v3, v203, s39, v202
	v_add_u32_e32 v203, 32, v200
	v_mad_u32_u24 v4, v203, s39, v202
	v_add_u32_e32 v203, 48, v200
	v_mad_u32_u24 v5, v203, s39, v202
	s_lshl_b32 s51, s58, 4
	v_add_u32_e32 v203, s51, v200
	v_mad_u32_u24 v248, v203, s39, v202
	v_lshlrev_b32_e32 v160, 2, v201
	v_sub_u32_e32 v160, v160, v203
	v_mul_u32_u24_e32 v249, 0xa00, v203
	v_lshl_add_u32 v249, v201, 3, v249
	v_lshrrev_b32_e32 v203, 3, v179
	s_lshl_b32 s51, s58, 4
	v_add_u32_e32 v203, s51, v203
	v_and_b32_e32 v202, 7, v179
	v_lshlrev_b32_e32 v202, 4, v202
	v_mad_u32_u24 v6, v203, s39, v202
	v_add_u32_e32 v200, 8, v203
	v_mad_u32_u24 v7, v200, s39, v202
	s_movk_i32 s57, 0x90
	v_mad_u32_u24 v158, v203, s57, v183
	v_add_u32_e32 v158, v158, v202
	v_and_b32_e32 v200, 15, v179
	v_mad_u32_u24 v8, v200, s57, v183
	v_lshl_add_u32 v8, v201, 4, v8
	v_lshrrev_b32_e32 v203, 2, v179
	v_mad_u32_u24 v159, v203, s57, v183
	v_and_b32_e32 v203, 3, v179
	v_lshl_add_u32 v159, v203, 3, v159
	v_add_u32_e32 v159, 0x2400, v159
	v_xor_b32_e32 v174, 16, v179
	v_lshlrev_b32_e32 v174, 2, v174
	v_xor_b32_e32 v175, 32, v179
	v_lshlrev_b32_e32 v175, 2, v175
	s_mul_i32 s51, s60, s38
	s_add_u32 s51, s51, s40
	s_mul_i32 s56, s51, 0x2800
	s_add_u32 s56, s56, s53
	s_add_u32 s42, s0, s56
	s_addc_u32 s43, s1, 0
	global_load_dwordx4 v[10:13], v248, s[42:43]
	global_load_dwordx4 v[14:17], v248, s[42:43] offset:64
	v_readlane_b32 s48, v252, 7
	v_readlane_b32 s49, v252, 8
	s_mul_i32 s56, s38, 0xa00
	s_lshl_b32 s57, s37, 7
	s_add_u32 s56, s56, s57
	s_add_u32 s56, s56, 0x11a80600
	s_nop 2
	s_add_u32 s48, s48, s56
	s_addc_u32 s49, s49, 0
	v_readlane_b32 s18, v252, 27
	v_readlane_b32 s19, v252, 28
	s_or_b32 s56, s92, s37
	s_lshl_b32 s56, s56, 2
	s_nop 3
	s_add_u32 s18, s18, s56
	s_addc_u32 s19, s19, 0
	s_load_dword s56, s[18:19], 0x0
	v_cmp_gt_u32_e32 vcc, 16, v179
	v_cndmask_b32_e64 v177, 0, 1.0, vcc
	s_waitcnt lgkmcnt(0)
	v_mov_b32_e32 v176, s56
	v_mov_b32_e32 v138, 0
	v_mov_b32_e32 v139, 0
	v_mov_b32_e32 v140, 0
	v_mov_b32_e32 v141, 0
	v_mov_b32_e32 v142, 0
	v_mov_b32_e32 v143, 0
	v_mov_b32_e32 v144, 0
	v_mov_b32_e32 v145, 0
	v_mov_b32_e32 v146, 0
	v_mov_b32_e32 v147, 0
	v_mov_b32_e32 v148, 0
	v_mov_b32_e32 v149, 0
	v_mov_b32_e32 v150, 0
	v_mov_b32_e32 v151, 0
	v_mov_b32_e32 v152, 0
	v_mov_b32_e32 v153, 0
	s_sub_u32 s50, s38, 128
	s_cmp_ge_i32 s50, 0
	s_cselect_b32 s56, 1, 0
	s_cmp_lt_i32 s50, s41
	s_cselect_b32 s57, 1, 0
	s_and_b32 s2, s56, s57
	s_cmp_eq_u32 s2, 1
	s_cselect_b32 s50, s50, s38
	s_mul_i32 s50, s50, s60
	s_add_u32 s50, s50, s40
	s_mul_i32 s50, s50, 0x2800
	s_add_u32 s56, s50, s54
	s_add_u32 s44, s0, s56
	s_addc_u32 s45, s1, 0
	s_add_u32 s56, s50, s55
	s_add_u32 s46, s0, s56
	s_addc_u32 s47, s1, 0
	global_load_dwordx4 v[50:53], v6, s[44:45]
	global_load_dwordx4 v[54:57], v7, s[44:45]
	global_load_dwordx4 v[58:61], v6, s[46:47]
	global_load_dwordx4 v[62:65], v7, s[46:47]
	s_sub_u32 s50, s38, 64
	s_cmp_ge_i32 s50, 0
	s_cselect_b32 s56, 1, 0
	s_cmp_lt_i32 s50, s41
	s_cselect_b32 s57, 1, 0
	s_and_b32 s3, s56, s57
	s_cmp_eq_u32 s3, 1
	s_cselect_b32 s50, s50, s38
	s_mul_i32 s50, s50, s60
	s_add_u32 s50, s50, s40
	s_mul_i32 s50, s50, 0x2800
	s_add_u32 s56, s50, s54
	s_add_u32 s44, s0, s56
	s_addc_u32 s45, s1, 0
	s_add_u32 s56, s50, s55
	s_add_u32 s46, s0, s56
	s_addc_u32 s47, s1, 0
	global_load_dwordx4 v[66:69], v6, s[44:45]
	global_load_dwordx4 v[70:73], v7, s[44:45]
	global_load_dwordx4 v[74:77], v6, s[46:47]
	global_load_dwordx4 v[78:81], v7, s[46:47]
	s_waitcnt vmcnt(4)
	s_barrier
	ds_write_b128 v158, v[50:53] offset:0
	ds_write_b128 v158, v[54:57] offset:1152
	ds_write_b128 v158, v[58:61] offset:9216
	ds_write_b128 v158, v[62:65] offset:10368
	s_waitcnt lgkmcnt(0)
	s_barrier
	s_add_u32 s50, s38, 0
	s_cmp_ge_i32 s50, 0
	s_cselect_b32 s56, 1, 0
	s_cmp_lt_i32 s50, s41
	s_cselect_b32 s57, 1, 0
	s_and_b32 s4, s56, s57
	s_cmp_eq_u32 s4, 1
	s_cselect_b32 s50, s50, s38
	s_mul_i32 s50, s50, s60
	s_add_u32 s50, s50, s40
	s_mul_i32 s50, s50, 0x2800
	s_add_u32 s56, s50, s54
	s_add_u32 s44, s0, s56
	s_addc_u32 s45, s1, 0
	s_add_u32 s56, s50, s55
	s_add_u32 s46, s0, s56
	s_addc_u32 s47, s1, 0
	global_load_dwordx4 v[50:53], v6, s[44:45]
	global_load_dwordx4 v[54:57], v7, s[44:45]
	global_load_dwordx4 v[58:61], v6, s[46:47]
	global_load_dwordx4 v[62:65], v7, s[46:47]
	s_cmp_eq_u32 s2, 1
	s_cbranch_scc0 .Lat1_kb0_end
; DI float grp16_sum(float v) { v += __shfl_xor(v, 1); v += __shfl_xor(v, 2); v += __shfl_xor(v, 4); v += __shfl_xor(v, 8); return v; }
; DI float grp16_max(float v) { v = fmaxf(v, __shfl_xor(v, 1)); v = fmaxf(v, __shfl_xor(v, 2)); v = fmaxf(v, __shfl_xor(v, 4)); v = fmaxf(v, __shfl_xor(v, 8)); return v; }
; template <int NKB>
; DI void attn_unit(const Params& p, int l, int mode, int grp, int head, int r0, int dil, int i0, int sub_len, int W, h16* lds) {
;     ...
;     mm64(Qi, Ki, S, w, lane);
;     float mx[4], al[4], rsum[4];
;     bool vm[4][4];
; #pragma unroll
;     for (int rg = 0; rg < 4; ++rg) {
;       const int row = 16 * w + 4 * q + rg;
;       float m_ = -1e30f;
; #pragma unroll
;       for (int nt = 0; nt < 4; ++nt) {
;         const int key = 16 * nt + r;
;         const int delta = row - key + W - 64 * kb;
;         const bool ok = inr && (delta >= -W) && (delta <= W);
;         vm[nt][rg] = ok;
;         float s = S[nt][rg] * 0.125f;
;         S[nt][rg] = s;
;         if (ok) m_ = fmaxf(m_, s);
;       }
;       mx[rg] = grp16_max(m_);
;     }
; #pragma unroll
;     for (int rg = 0; rg < 4; ++rg) {
;       const float mn = fmaxf(mrow[rg], mx[rg]);
;       al[rg] = __expf(mrow[rg] - mn);
;       mrow[rg] = mn;
;       float rs_ = 0.f;
; #pragma unroll
;       for (int nt = 0; nt < 4; ++nt) {
;         float pv = vm[nt][rg] ? __expf(S[nt][rg] - mn) : 0.f;
;         rs_ += pv;
;         Pi[(16 * w + 4 * q + rg) * LDH + 16 * nt + r] = (h16)pv;
;       }
;       rsum[rg] = grp16_sum(rs_);
;       lsum[rg] = lsum[rg] * al[rg] + rsum[rg];
;     }
; #pragma unroll
;     for (int et = 0; et < 4; ++et)
; #pragma unroll
;       for (int rg = 0; rg < 4; ++rg) O[et][rg] *= al[rg];
;     __syncthreads();
;     mm64(Pi, Vt, O, w, lane);
	ds_read_b128 v[18:21], v8 offset:0
	ds_read_b128 v[22:25], v8 offset:64
	ds_read_b128 v[26:29], v8 offset:2304
	ds_read_b128 v[30:33], v8 offset:2368
	ds_read_b128 v[34:37], v8 offset:4608
	ds_read_b128 v[38:41], v8 offset:4672
	ds_read_b128 v[42:45], v8 offset:6912
	ds_read_b128 v[46:49], v8 offset:6976
	ds_read_b64_tr_b16 v[216:217], v159
	ds_read_b64_tr_b16 v[218:219], v159 offset:2304
	ds_read_b64_tr_b16 v[220:221], v159 offset:4608
	ds_read_b64_tr_b16 v[222:223], v159 offset:6912
	ds_read_b64_tr_b16 v[224:225], v159 offset:32
	ds_read_b64_tr_b16 v[226:227], v159 offset:2336
	ds_read_b64_tr_b16 v[228:229], v159 offset:4640
	ds_read_b64_tr_b16 v[230:231], v159 offset:6944
	ds_read_b64_tr_b16 v[232:233], v159 offset:64
	ds_read_b64_tr_b16 v[234:235], v159 offset:2368
	ds_read_b64_tr_b16 v[236:237], v159 offset:4672
	ds_read_b64_tr_b16 v[238:239], v159 offset:6976
	ds_read_b64_tr_b16 v[240:241], v159 offset:96
	ds_read_b64_tr_b16 v[242:243], v159 offset:2400
	ds_read_b64_tr_b16 v[244:245], v159 offset:4704
	ds_read_b64_tr_b16 v[246:247], v159 offset:7008
	s_waitcnt lgkmcnt(15)
	v_mfma_f32_16x16x32_f16 v[114:117], v[18:21], v[10:13], 0
	v_mfma_f32_16x16x32_f16 v[118:121], v[26:29], v[10:13], 0
	v_mfma_f32_16x16x32_f16 v[122:125], v[34:37], v[10:13], 0
	v_mfma_f32_16x16x32_f16 v[126:129], v[42:45], v[10:13], 0
	v_mfma_f32_16x16x32_f16 v[114:117], v[22:25], v[14:17], v[114:117]
	v_mfma_f32_16x16x32_f16 v[118:121], v[30:33], v[14:17], v[118:121]
	v_mfma_f32_16x16x32_f16 v[122:125], v[38:41], v[14:17], v[122:125]
	v_mfma_f32_16x16x32_f16 v[126:129], v[46:49], v[14:17], v[126:129]
	s_nop 7
	s_nop 7
	v_mul_f32_e32 v114, 0x3e000000, v114
	v_mul_f32_e32 v115, 0x3e000000, v115
	v_mul_f32_e32 v116, 0x3e000000, v116
	v_mul_f32_e32 v117, 0x3e000000, v117
	v_mul_f32_e32 v118, 0x3e000000, v118
	v_mul_f32_e32 v119, 0x3e000000, v119
	v_mul_f32_e32 v120, 0x3e000000, v120
	v_mul_f32_e32 v121, 0x3e000000, v121
	v_mul_f32_e32 v122, 0x3e000000, v122
	v_mul_f32_e32 v123, 0x3e000000, v123
	v_mul_f32_e32 v124, 0x3e000000, v124
	v_mul_f32_e32 v125, 0x3e000000, v125
	v_mul_f32_e32 v126, 0x3e000000, v126
	v_mul_f32_e32 v127, 0x3e000000, v127
	v_mul_f32_e32 v128, 0x3e000000, v128
	v_mul_f32_e32 v129, 0x3e000000, v129
	v_mov_b32_e32 v200, 0xf149f2ca
	v_cmp_le_i32_e32 vcc, 0, v160
	v_cndmask_b32_e32 v114, v200, v114, vcc
	v_cmp_le_i32_e32 vcc, -1, v160
	v_cndmask_b32_e32 v115, v200, v115, vcc
	v_cmp_le_i32_e32 vcc, -2, v160
	v_cndmask_b32_e32 v116, v200, v116, vcc
	v_cmp_le_i32_e32 vcc, -3, v160
	v_cndmask_b32_e32 v117, v200, v117, vcc
	v_cmp_le_i32_e32 vcc, -16, v160
	v_cndmask_b32_e32 v118, v200, v118, vcc
	v_cmp_le_i32_e32 vcc, -17, v160
	v_cndmask_b32_e32 v119, v200, v119, vcc
	v_cmp_le_i32_e32 vcc, -18, v160
	v_cndmask_b32_e32 v120, v200, v120, vcc
	v_cmp_le_i32_e32 vcc, -19, v160
	v_cndmask_b32_e32 v121, v200, v121, vcc
	v_cmp_le_i32_e32 vcc, -32, v160
	v_cndmask_b32_e32 v122, v200, v122, vcc
	v_cmp_le_i32_e32 vcc, -33, v160
	v_cndmask_b32_e32 v123, v200, v123, vcc
	v_cmp_le_i32_e32 vcc, -34, v160
	v_cndmask_b32_e32 v124, v200, v124, vcc
	v_cmp_le_i32_e32 vcc, -35, v160
	v_cndmask_b32_e32 v125, v200, v125, vcc
	v_cmp_le_i32_e32 vcc, -48, v160
	v_cndmask_b32_e32 v126, v200, v126, vcc
	v_cmp_le_i32_e32 vcc, -49, v160
	v_cndmask_b32_e32 v127, v200, v127, vcc
	v_cmp_le_i32_e32 vcc, -50, v160
	v_cndmask_b32_e32 v128, v200, v128, vcc
	v_cmp_le_i32_e32 vcc, -51, v160
	v_cndmask_b32_e32 v129, v200, v129, vcc
	v_max3_f32 v179, v114, v115, v116
	v_max3_f32 v179, v179, v117, v118
	v_max3_f32 v179, v179, v119, v120
	v_max3_f32 v179, v179, v121, v122
	v_max3_f32 v179, v179, v123, v124
	v_max3_f32 v179, v179, v125, v126
	v_max3_f32 v179, v179, v127, v128
	v_max_f32_e32 v179, v179, v129
	ds_bpermute_b32 v201, v174, v179
	s_waitcnt lgkmcnt(0)
	v_max_f32_e32 v179, v179, v201
	ds_bpermute_b32 v201, v175, v179
	s_waitcnt lgkmcnt(0)
	v_max3_f32 v179, v179, v201, v176
	v_sub_f32_e32 v178, v176, v179
	v_mul_f32_e32 v178, 0x3fb8aa3b, v178
	v_exp_f32_e32 v178, v178
	v_mov_b32_e32 v176, v179
	v_mul_f32_e32 v202, 0xbfb8aa3b, v179
	v_mov_b32_e32 v203, 0x3fb8aa3b
	v_fma_f32 v114, v114, v203, v202
	v_fma_f32 v115, v115, v203, v202
	v_fma_f32 v116, v116, v203, v202
	v_fma_f32 v117, v117, v203, v202
	v_fma_f32 v118, v118, v203, v202
	v_fma_f32 v119, v119, v203, v202
	v_fma_f32 v120, v120, v203, v202
	v_fma_f32 v121, v121, v203, v202
	v_fma_f32 v122, v122, v203, v202
	v_fma_f32 v123, v123, v203, v202
	v_fma_f32 v124, v124, v203, v202
	v_fma_f32 v125, v125, v203, v202
	v_fma_f32 v126, v126, v203, v202
	v_fma_f32 v127, v127, v203, v202
	v_fma_f32 v128, v128, v203, v202
	v_fma_f32 v129, v129, v203, v202
	v_exp_f32_e32 v114, v114
	v_exp_f32_e32 v115, v115
	v_exp_f32_e32 v116, v116
	v_exp_f32_e32 v117, v117
	v_exp_f32_e32 v118, v118
	v_exp_f32_e32 v119, v119
	v_exp_f32_e32 v120, v120
	v_exp_f32_e32 v121, v121
	v_exp_f32_e32 v122, v122
	v_exp_f32_e32 v123, v123
	v_exp_f32_e32 v124, v124
	v_exp_f32_e32 v125, v125
	v_exp_f32_e32 v126, v126
	v_exp_f32_e32 v127, v127
	v_exp_f32_e32 v128, v128
	v_exp_f32_e32 v129, v129
	s_nop 0
	v_fma_f32 v177, v177, v178, v114
	v_add_f32_e32 v177, v177, v115
	v_add_f32_e32 v177, v177, v116
	v_add_f32_e32 v177, v177, v117
	v_add_f32_e32 v177, v177, v118
	v_add_f32_e32 v177, v177, v119
	v_add_f32_e32 v177, v177, v120
	v_add_f32_e32 v177, v177, v121
	v_add_f32_e32 v177, v177, v122
	v_add_f32_e32 v177, v177, v123
	v_add_f32_e32 v177, v177, v124
	v_add_f32_e32 v177, v177, v125
	v_add_f32_e32 v177, v177, v126
	v_add_f32_e32 v177, v177, v127
	v_add_f32_e32 v177, v177, v128
	v_add_f32_e32 v177, v177, v129
	v_cvt_pk_f16_f32 v130, v114, v115
	v_cvt_pk_f16_f32 v131, v116, v117
	v_cvt_pk_f16_f32 v132, v118, v119
	v_cvt_pk_f16_f32 v133, v120, v121
	v_cvt_pk_f16_f32 v134, v122, v123
	v_cvt_pk_f16_f32 v135, v124, v125
	v_cvt_pk_f16_f32 v136, v126, v127
	v_cvt_pk_f16_f32 v137, v128, v129
	v_pk_mul_f32 v[138:139], v[138:139], v[178:179] op_sel_hi:[1,0]
	v_pk_mul_f32 v[140:141], v[140:141], v[178:179] op_sel_hi:[1,0]
	v_pk_mul_f32 v[142:143], v[142:143], v[178:179] op_sel_hi:[1,0]
	v_pk_mul_f32 v[144:145], v[144:145], v[178:179] op_sel_hi:[1,0]
	v_pk_mul_f32 v[146:147], v[146:147], v[178:179] op_sel_hi:[1,0]
	v_pk_mul_f32 v[148:149], v[148:149], v[178:179] op_sel_hi:[1,0]
	v_pk_mul_f32 v[150:151], v[150:151], v[178:179] op_sel_hi:[1,0]
	v_pk_mul_f32 v[152:153], v[152:153], v[178:179] op_sel_hi:[1,0]
	s_nop 1
	v_mfma_f32_16x16x32_f16 v[138:141], v[216:219], v[130:133], v[138:141]
	v_mfma_f32_16x16x32_f16 v[142:145], v[224:227], v[130:133], v[142:145]
	v_mfma_f32_16x16x32_f16 v[146:149], v[232:235], v[130:133], v[146:149]
	v_mfma_f32_16x16x32_f16 v[150:153], v[240:243], v[130:133], v[150:153]
	v_mfma_f32_16x16x32_f16 v[138:141], v[220:223], v[134:137], v[138:141]
	v_mfma_f32_16x16x32_f16 v[142:145], v[228:231], v[134:137], v[142:145]
	v_mfma_f32_16x16x32_f16 v[146:149], v[236:239], v[134:137], v[146:149]
	v_mfma_f32_16x16x32_f16 v[150:153], v[244:247], v[134:137], v[150:153]
